# step 11 rebalance: gate WGs 3 rounds of gate_a GEMM, scan WGs run the 4th round after the scan
# baseline (speedup 1.0000x reference)
; #define LAUNDER_V(x) asm volatile("" : "+v"(x))
; #define PG8_BAR __builtin_amdgcn_s_barrier()
; template <class Epi>
; __device__ __forceinline__ void gemm_phase(LAS unsigned char* lds, const Gemm g, const StaticOrder& S, const Epi& E) {
;     int tid = threadIdx.x; LAUNDER_V(tid);
;     const int wid = __builtin_amdgcn_readfirstlane(tid >> 6), lane = tid & 63, wr = wid >> 2, wc = wid & 3, fr = lane & 15, fq = lane >> 4;
;     const int K = g.K, nt = K / BK;
;     unsigned voffA[2], voffB[2];
; #pragma unroll
;     for (int i = 0; i < 2; ++i) { int R, C; stage_rc(tid * 16 + i * 8192, R, C); const int Rb = Epi::PERM ? ((R & ~31) + perm32(R & 31)) : R;
;         voffA[i] = (unsigned)(R * g.lda + C) * 2u; voffB[i] = (unsigned)(Rb * K + C) * 2u; }
;     const size_t kstep = (size_t)(BK * 2);
;     const size_t hstepA = (size_t)HALF * g.lda * 2, hstepB = (size_t)HALF * K * 2;
;     const size_t tstepA = 2 * hstepA, tstepB = 2 * hstepB;
;     const unsigned ldsw = (unsigned)wid * 1024u;
;     const int aoff = lds_byte(wr * 64 + fr, fq * 8), boff = lds_byte(wc * 32 + fr, fq * 8);
;     ...
;     Unit cur, nxt; int ui = 0;
;     if (!S.next(0, cur)) return;
;     f32x4 acc[2][2][4][2];
; #pragma unroll
;     for (int a = 0; a < 2; ++a)
; #pragma unroll
;         for (int b = 0; b < 2; ++b)
; #pragma unroll
;             for (int m = 0; m < 4; ++m)
; #pragma unroll
;                 for (int n = 0; n < 2; ++n) acc[a][b][m][n] = (f32x4){0.f, 0.f, 0.f, 0.f};
;     h16x8 At[4][2], B0[2][2], B1[2][2];
;     const char* cA = (const char*)g.A + (size_t)cur.pm * tstepA; const char* cB = (const char*)g.Bt + (size_t)cur.pn * tstepB;
;     PG8_STAGE(PG8_SB(0, 0), cB, voffB); PG8_STAGE(PG8_SB(0, 1), cB + hstepB, voffB); PG8_STAGE(PG8_SA(0, 0), cA, voffA); PG8_STAGE(PG8_SA(0, 1), cA + hstepA, voffA);
;     if (wr == 1) PG8_BAR;
;     PG8_WAIT_V(2); PG8_BAR;
;     PG8_STAGE(PG8_SB(1, 0), cB + kstep, voffB); PG8_STAGE(PG8_SA(1, 0), cA + kstep, voffA); PG8_STAGE(PG8_SB(1, 1), cB + hstepB + kstep, voffB);
;     PG8_WAIT_V(6); PG8_BAR;
; __global__ void __launch_bounds__(512, 2) fwd_mega(Params p) {
;     ...
;         } else if (sl == 11) {
;             if (bid < 128) {
;                 phase_scan(Pdn, Tg, QKg, GC, BETA, LSE, lds);
;             } else {
;                 pg8::Gemm gm{XN, Wg, M_TOK, 1024, 1024, 1024}; pg8::StaticOrder S; S.init(M_TOK, 1024, G - 128, bid - 128);
.LBB0_198:
	s_add_u32 s80, s86, 0x1fdc0000
	s_addc_u32 s81, s87, 0
	s_add_u32 s3, s86, 0x1fec0000
	v_writelane_b32 v255, s3, 36
	s_addc_u32 s3, s87, 0
	v_writelane_b32 v255, s3, 38
	v_readlane_b32 s3, v254, 63
	s_and_b32 s27, 0xffff, s3
	s_cmp_gt_i32 s27, 10
	s_mov_b64 s[4:5], -1
	s_cbranch_scc0 .LBB0_285
	v_writelane_b32 v255, s4, 18
	s_cmp_eq_u32 s27, 11
	s_nop 0
	v_writelane_b32 v255, s5, 19
	s_cbranch_scc0 .LBB0_284
	s_cmpk_gt_i32 s2, 0x7f
	s_cselect_b32 s3, 0, 1
	s_nop 3
	v_writelane_b32 v255, s3, 60
	s_movk_i32 s3, 0x200
	s_cselect_b32 s3, 0x180, s3
	s_nop 3
	v_writelane_b32 v255, s3, 61
	s_mov_b64 s[0:1], -1
	s_cbranch_scc0 .LBB0_243
	s_add_i32 s3, s2, 0xffffff80
	v_mov_b32_e32 v14, v192
	s_cmpk_gt_u32 s3, 0x1ff
	v_readfirstlane_b32 s4, v14
	s_cbranch_scc1 .LBB0_227
.Lgemm11_body:
	v_lshlrev_b32_e32 v0, 4, v14
	v_add_u32_e32 v1, 0x2000, v0
	v_ashrrev_i32_e32 v2, 31, v1
	v_lshrrev_b32_e32 v2, 22, v2
	v_add_u32_e32 v2, v1, v2
	v_ashrrev_i32_e32 v8, 10, v2
	v_mul_i32_i24_e32 v2, 0x400, v8
	v_sub_u32_e32 v1, v1, v2
	v_lshrrev_b32_e32 v2, 4, v1
	v_bitop3_b32 v1, v2, v1, 32 bitop3:0x6c
	v_ashrrev_i32_e32 v2, 31, v1
	v_lshrrev_b32_e32 v2, 26, v2
	v_add_u32_e32 v2, v1, v2
	v_lshlrev_b32_e32 v3, 3, v8
	v_ashrrev_i32_e32 v9, 6, v2
	v_and_b32_e32 v3, -16, v3
	v_add_u32_e32 v3, v9, v3
	v_and_b32_e32 v4, 3, v9
	s_mov_b32 s0, 0x1fffe0
	v_lshrrev_b32_e32 v5, 2, v3
	v_lshlrev_b32_e32 v6, 1, v3
	v_and_b32_e32 v2, 0xc0, v2
	v_and_or_b32 v4, v3, s0, v4
	v_and_b32_e32 v5, 4, v5
	v_and_b32_e32 v6, 24, v6
	v_sub_u32_e32 v1, v1, v2
	v_or3_b32 v4, v4, v5, v6
	v_lshlrev_b32_e32 v5, 5, v8
	v_ashrrev_i16_sdwa v1, v195, sext(v1) dst_sel:DWORD dst_unused:UNUSED_PAD src0_sel:DWORD src1_sel:BYTE_0
	v_and_b32_e32 v5, 32, v5
	v_bfe_i32 v10, v1, 0, 16
	v_add_lshl_u32 v1, v5, v10, 1
	v_lshl_add_u32 v130, v4, 11, v1
	v_lshl_add_u32 v132, v3, 11, v1
	v_bfe_i32 v1, v14, 27, 1
	v_lshrrev_b32_e32 v1, 22, v1
	v_add_u32_e32 v1, v0, v1
	v_and_b32_e32 v1, 0xfffffc00, v1
	v_sub_u32_e32 v0, v0, v1
	v_lshrrev_b32_e32 v1, 4, v0
	v_ashrrev_i32_e32 v2, 31, v14
	v_bitop3_b32 v0, v1, v0, 32 bitop3:0x6c
	v_lshrrev_b32_e32 v2, 26, v2
	v_ashrrev_i32_e32 v1, 31, v0
	v_add_u32_e32 v2, v14, v2
	v_lshrrev_b32_e32 v1, 26, v1
	v_ashrrev_i32_e32 v12, 6, v2
	v_add_u32_e32 v1, v0, v1
	v_lshlrev_b32_e32 v2, 3, v12
	v_ashrrev_i32_e32 v11, 6, v1
	v_and_b32_e32 v2, -16, v2
	v_add_u32_e32 v2, v11, v2
	v_and_b32_e32 v3, 3, v11
	v_and_or_b32 v3, v2, s0, v3
	s_lshr_b32 s0, s3, 3
	s_lshl_b32 s1, s2, 6
	s_or_b32 s0, s1, s0
	s_lshr_b32 s0, s0, 2
	v_lshrrev_b32_e32 v4, 2, v2
	v_lshlrev_b32_e32 v5, 1, v2
	v_and_b32_e32 v1, 0xc0, v1
	s_and_b32 s0, s0, 0x78
	s_bfe_u32 s1, s3, 0x30003
	s_ashr_i32 s6, s4, 6
	v_and_b32_e32 v4, 4, v4
	v_and_b32_e32 v5, 24, v5
	v_sub_u32_e32 v0, v0, v1
	s_or_b32 s68, s0, s1
	s_bfe_u32 s7, s3, 0x20006
	s_ashr_i32 s5, s4, 8
	s_lshl_b32 s24, s6, 10
	v_or3_b32 v3, v3, v4, v5
	v_lshlrev_b32_e32 v4, 5, v12
	v_ashrrev_i16_sdwa v0, v195, sext(v0) dst_sel:DWORD dst_unused:UNUSED_PAD src0_sel:DWORD src1_sel:BYTE_0
	s_lshl_b32 s8, s68, 19
	s_lshl_b32 s0, s7, 19
	v_readlane_b32 s10, v255, 5
	v_and_b32_e32 v4, 32, v4
	v_bfe_i32 v13, v0, 0, 16
	v_readlane_b32 s11, v255, 6
	s_add_u32 s18, s10, s0
	v_add_lshl_u32 v0, v4, v13, 1
	s_addc_u32 s19, s11, 0
	s_add_i32 s28, s24, 0
	v_lshl_add_u32 v134, v3, 11, v0
	s_add_i32 m0, s28, 0x10000
	v_lshl_add_u32 v136, v2, 11, v0
	global_load_lds_dwordx4 v134, s[18:19]
	s_add_i32 m0, s28, 0x12000
	s_add_u32 s0, s18, 0x40000
	global_load_lds_dwordx4 v130, s[18:19]
	s_addc_u32 s1, s19, 0
	s_add_i32 m0, s28, 0x14000
	v_mov_b32_e32 v135, v33
	global_load_lds_dwordx4 v134, s[0:1]
	s_add_i32 m0, s28, 0x16000
	s_add_u32 s20, s84, s8
	s_addc_u32 s21, s85, 0
	s_add_i32 s29, s28, 0x2000
	global_load_lds_dwordx4 v130, s[0:1]
	s_mov_b32 m0, s28
	s_add_u32 s0, s20, 0x40000
	global_load_lds_dwordx4 v136, s[20:21]
	s_mov_b32 m0, s29
	s_addc_u32 s1, s21, 0
	s_add_i32 s30, s28, 0x4000
	global_load_lds_dwordx4 v132, s[20:21]
	s_mov_b32 m0, s30
	s_add_i32 s31, s28, 0x6000
	global_load_lds_dwordx4 v136, s[0:1]
	s_mov_b32 m0, s31
	v_mov_b32_e32 v131, v33
	global_load_lds_dwordx4 v132, s[0:1]
	v_mov_b32_e32 v137, v33
	v_mov_b32_e32 v133, v33
	s_cmp_eq_u32 s5, 1
	v_lshl_add_u64 v[6:7], s[18:19], 0, v[134:135]
	v_lshl_add_u64 v[4:5], s[18:19], 0, v[130:131]
	v_lshl_add_u64 v[0:1], s[20:21], 0, v[136:137]
	s_cselect_b64 s[0:1], -1, 0
	s_cmp_lg_u32 s5, 1
	v_lshl_add_u64 v[2:3], s[20:21], 0, v[132:133]
	s_cbranch_scc1 .LBB0_204
	s_barrier

;     __device__ bool next(int i, Unit& u) const {
;         const long L = (long)i * G + c; if (L >= nwg) return false;
;         int wgid = (int)L; { const int q = nwg / NXCD, r = nwg % NXCD, xcd = wgid % NXCD, off = wgid / NXCD; wgid = (xcd < r ? xcd * (q + 1) : r * (q + 1) + (xcd - r) * q) + off; }
;         const int nig = WGM * nN, gid = wgid / nig, fm = gid * WGM, gsz = (nM - fm) < WGM ? (nM - fm) : WGM;
;         u.pm = fm + ((wgid % nig) % gsz); u.pn = (wgid % nig) / gsz; return true;
; template <class Epi>
; __device__ __forceinline__ void gemm_phase(LAS unsigned char* lds, const Gemm g, const StaticOrder& S, const Epi& E) {
;     ...
;         const bool has_next = S.next(ui + 1, nxt);
.LBB0_207:
	s_add_i32 s55, s55, 1
	v_readlane_b32 s4, v253, 54
	v_readlane_b32 s11, v253, 55
	s_mul_i32 s4, s55, s4
	s_mul_hi_u32 s5, s55, s11
	s_add_i32 s5, s5, s4
	s_mul_i32 s4, s55, s11
	s_add_u32 s14, s4, s3
	s_addc_u32 s15, s5, 0
	v_readlane_b32 s4, v255, 61
	s_nop 3
	s_cmp_lt_u32 s14, s4
	s_cselect_b64 s[4:5], -1, 0
	s_cbranch_scc0 .LBB0_213
	s_ashr_i32 s10, s14, 31
	s_lshr_b32 s10, s10, 29
	s_add_i32 s12, s14, s10
	s_and_b32 s10, s12, -8
	s_sub_i32 s13, s14, s10
	s_cmp_gt_i32 s13, -1
	s_mov_b64 s[10:11], -1
	s_cbranch_scc0 .LBB0_210
	s_lshl_b32 s14, s13, 6
	s_mov_b64 s[10:11], 0

; __global__ void __launch_bounds__(512, 2) fwd_mega(Params p) {
;     ...
;             if (bid < 128) {
;                 phase_scan(Pdn, Tg, QKg, GC, BETA, LSE, lds);
;             } else {
;                 pg8::Gemm gm{XN, Wg, M_TOK, 1024, 1024, 1024}; pg8::StaticOrder S; S.init(M_TOK, 1024, G - 128, bid - 128);
.Lgemm11_scan_entry:
	s_mov_b32 s3, 0
	s_nop 3
	v_writelane_b32 v255, s3, 60
	s_waitcnt vmcnt(0) lgkmcnt(0)
	s_barrier
	s_add_i32 s3, s2, 0x180
	v_mov_b32_e32 v14, v192
	s_nop 1
	v_readfirstlane_b32 s4, v14
	s_branch .Lgemm11_body

; __global__ void __launch_bounds__(512, 2) fwd_mega(Params p) {
;     ...
;             if (bid < 128) {
;                 phase_scan(Pdn, Tg, QKg, GC, BETA, LSE, lds);
;             } else {
;                 pg8::Gemm gm{XN, Wg, M_TOK, 1024, 1024, 1024}; pg8::StaticOrder S; S.init(M_TOK, 1024, G - 128, bid - 128);
;                 pg8::EpiStore E{GATE_A, 1024, BD, 4, 1, (h16*)nullptr}; pg8::gemm_phase(ldsl, gm, S, E);
.LBB0_283:
	v_readlane_b32 s3, v255, 60
	s_nop 3
	s_cmp_eq_u32 s3, 0
	s_cbranch_scc0 .Lgemm11_scan_entry
	s_mov_b64 s[4:5], 0
	v_writelane_b32 v255, s4, 18
	s_mov_b64 s[0:1], -1
	s_nop 0
	v_writelane_b32 v255, s5, 19
